# attention K tiles via full-line LDS-DMA + ds_read fragments (mixA far/pass2, MoBA partials/finisher)
# speedup vs baseline: 1.0697x; 1.0169x over previous
.LBB0_490:
	s_ashr_i32 s0, s42, 2
	s_and_b32 s0, s0, -8
	v_readlane_b32 s12, v254, 38
	s_add_i32 s38, s0, s12
	s_mul_hi_i32 s0, s38, 0x2aaaaaab
	s_lshr_b32 s1, s0, 31
	s_add_i32 s0, s0, s1
	s_mul_i32 s1, s0, 6
	s_sub_i32 s43, s38, s1
	s_lshl_b32 s1, s42, 7
	s_and_b32 s40, s1, 0xe00
	s_lshl_b32 s1, s42, 2
	v_mov_b32_e32 v0, v199
	s_and_b32 s1, s1, 12
	v_add_u32_e32 v162, s1, v161
	v_and_b32_e32 v175, 31, v0
	v_and_b32_e32 v174, 63, v0
	v_bfe_u32 v10, v0, 5, 1
	v_lshl_or_b32 v0, v175, 4, s40
	v_add_u32_e32 v2, v0, v162
	s_ashr_i32 s1, s0, 31
	s_lshl_b64 s[36:37], s[0:1], 12
	v_ashrrev_i32_e32 v3, 31, v2
	v_lshl_add_u64 v[158:159], s[36:37], 0, v[2:3]
	v_mov_b64_e32 v[2:3], s[66:67]
	v_mad_u64_u32 v[2:3], s[0:1], v158, s80, v[2:3]
	s_lshl_b32 s0, s43, 6
	v_mad_i32_i24 v3, v159, s80, v3
	s_ashr_i32 s1, s0, 31
	v_lshl_add_u64 v[4:5], s[0:1], 1, v[2:3]
	v_lshlrev_b32_e32 v0, 4, v10
	v_lshlrev_b32_e32 v160, 3, v10
	v_lshl_add_u64 v[4:5], v[4:5], 0, v[0:1]
	s_add_i32 s30, s0, 0x180
	s_ashr_i32 s39, s38, 31
	v_readlane_b32 s44, v253, 2
	global_load_dwordx4 v[82:85], v[4:5], off
	global_load_dwordx4 v[86:89], v[4:5], off offset:32
	global_load_dwordx4 v[90:93], v[4:5], off offset:64
	global_load_dwordx4 v[94:97], v[4:5], off offset:96
	v_or_b32_e32 v4, s30, v160
	s_lshl_b64 s[38:39], s[38:39], 19
	s_lshl_b32 s30, s40, 3
	v_readlane_b32 s48, v253, 6
	v_ashrrev_i32_e32 v163, 31, v162
	v_readlane_b32 s49, v253, 7
	s_add_u32 s38, s48, s38
	v_lshlrev_b64 v[6:7], 15, v[162:163]
	s_addc_u32 s39, s49, s39
	v_mov_b32_e32 v5, v1
	v_lshl_add_u64 v[6:7], s[38:39], 0, v[6:7]
	v_lshlrev_b64 v[4:5], 1, v[4:5]
	v_lshl_add_u64 v[8:9], v[6:7], 0, s[30:31]
	v_lshlrev_b32_e32 v0, 5, v174
	v_lshl_add_u64 v[2:3], v[2:3], 0, v[4:5]
	v_lshl_add_u64 v[8:9], v[8:9], 0, v[0:1]
	v_and_b32_e32 v238, 63, v199
	v_lshrrev_b32_e32 v239, 3, v238
	v_and_b32_e32 v240, 31, v238
	v_sub_u32_e32 v224, v239, v240
	v_add_u32_e32 v225, 8, v224
	v_add_u32_e32 v226, 16, v224
	v_add_u32_e32 v227, 24, v224
	v_lshrrev_b32_e32 v241, 5, v238
	v_and_b32_e32 v242, 7, v238
	v_lshrrev_b32_e32 v243, 4, v238
	v_xor_b32_e32 v228, v242, v243
	v_xor_b32_e32 v229, 4, v228
	v_sub_u32_e32 v228, v228, v241
	v_sub_u32_e32 v229, v229, v241
	v_lshlrev_b32_e32 v228, 4, v228
	v_lshlrev_b32_e32 v229, 4, v229
	v_lshrrev_b32_e32 v250, 6, v199
	v_lshlrev_b32_e32 v250, 13, v250
	v_bfe_u32 v251, v238, 1, 3
	v_xor_b32_e32 v251, v251, v241
	v_lshlrev_b32_e32 v251, 4, v251
	v_lshl_add_u32 v251, v240, 7, v251
	v_add_u32_e32 v234, v250, v251
	v_xor_b32_e32 v235, 0x20, v234
	v_xor_b32_e32 v236, 0x40, v234
	v_xor_b32_e32 v237, 0x60, v234
	v_readfirstlane_b32 s98, v250
	s_mov_b32 s99, 0x1c000
	s_add_u32 m0, s98, 0x0
	v_mad_i64_i32 v[232:233], s[100:101], v224, s99, v[2:3]
	v_add_u32_e32 v232, v228, v232
	global_load_lds_dwordx4 v[232:233], off
	s_add_u32 m0, s98, 0x400
	v_mad_i64_i32 v[232:233], s[100:101], v225, s99, v[2:3]
	v_add_u32_e32 v232, v229, v232
	global_load_lds_dwordx4 v[232:233], off
	s_add_u32 m0, s98, 0x800
	v_mad_i64_i32 v[232:233], s[100:101], v226, s99, v[2:3]
	v_add_u32_e32 v232, v228, v232
	global_load_lds_dwordx4 v[232:233], off
	s_add_u32 m0, s98, 0xc00
	v_mad_i64_i32 v[232:233], s[100:101], v227, s99, v[2:3]
	v_add_u32_e32 v232, v229, v232
	global_load_lds_dwordx4 v[232:233], off
	global_load_dwordx4 v[110:113], v[8:9], off
	global_load_dwordx4 v[106:109], v[8:9], off offset:16
	global_load_dwordx4 v[102:105], v[8:9], off offset:2048
	global_load_dwordx4 v[98:101], v[8:9], off offset:2064
	v_lshl_or_b32 v163, v10, 2, v213
	v_lshl_add_u64 v[164:165], v[6:7], 0, v[0:1]
	v_lshl_add_u64 v[166:167], s[66:67], 0, v[4:5]
	v_mov_b32_e32 v2, v1
	v_mov_b32_e32 v3, v1
	v_mov_b32_e32 v4, v1
	v_mov_b32_e32 v5, v1
	v_mov_b32_e32 v6, v1
	v_mov_b32_e32 v7, v1
	v_mov_b32_e32 v8, v1
	v_mov_b32_e32 v9, v1
	v_mov_b32_e32 v10, v1
	v_mov_b32_e32 v11, v1
	v_mov_b32_e32 v12, v1
	v_mov_b32_e32 v13, v1
	v_mov_b32_e32 v14, v1
	v_mov_b32_e32 v15, v1
	v_mov_b32_e32 v16, v1
	v_mov_b32_e32 v17, v1
	v_mov_b32_e32 v18, v1
	v_mov_b32_e32 v19, v1
	v_mov_b32_e32 v20, v1
	v_mov_b32_e32 v21, v1
	v_mov_b32_e32 v22, v1
	v_mov_b32_e32 v23, v1
	v_mov_b32_e32 v24, v1
	v_mov_b32_e32 v25, v1
	v_mov_b32_e32 v26, v1
	v_mov_b32_e32 v27, v1
	v_mov_b32_e32 v28, v1
	v_mov_b32_e32 v29, v1
	v_mov_b32_e32 v30, v1
	v_mov_b32_e32 v31, v1
	v_mov_b32_e32 v0, v1
	v_mov_b64_e32 v[32:33], v[30:31]
	s_lshr_b32 s30, s40, 4
	s_mov_b32 s44, 0
	v_mov_b32_e32 v173, 0xc61c4000
	v_mov_b32_e32 v171, 0
	v_mov_b64_e32 v[30:31], v[28:29]
	v_mov_b64_e32 v[28:29], v[26:27]
	v_mov_b64_e32 v[26:27], v[24:25]
	v_mov_b64_e32 v[24:25], v[22:23]
	v_mov_b64_e32 v[22:23], v[20:21]
	v_mov_b64_e32 v[20:21], v[18:19]
	v_mov_b64_e32 v[18:19], v[16:17]
	v_mov_b64_e32 v[16:17], v[14:15]
	v_mov_b64_e32 v[14:15], v[12:13]
	v_mov_b64_e32 v[12:13], v[10:11]
	v_mov_b64_e32 v[10:11], v[8:9]
	v_mov_b64_e32 v[8:9], v[6:7]
	v_mov_b64_e32 v[6:7], v[4:5]
	v_mov_b64_e32 v[4:5], v[2:3]
	v_mov_b64_e32 v[2:3], v[0:1]
	v_readlane_b32 s13, v254, 39
	v_readlane_b32 s45, v253, 3
	v_readlane_b32 s46, v253, 4
	v_readlane_b32 s47, v253, 5
	v_readlane_b32 s50, v253, 8
	v_readlane_b32 s51, v253, 9
	v_readlane_b32 s52, v253, 10
	v_readlane_b32 s53, v253, 11
	v_readlane_b32 s54, v253, 12
	v_readlane_b32 s55, v253, 13
	v_readlane_b32 s56, v253, 14
	v_readlane_b32 s57, v253, 15
	v_readlane_b32 s58, v253, 16
	v_readlane_b32 s59, v253, 17
	s_branch .LBB0_494

.LBB0_498:
	s_cmp_gt_i32 s45, -1
	s_cselect_b64 s[38:39], -1, 0
	s_cmp_lt_i32 s45, 0
	s_cselect_b32 s41, s44, s45
	s_lshl_b32 s41, s41, 5
	s_sub_i32 s41, s30, s41
	v_or_b32_e32 v0, s41, v175
	v_lshl_add_u32 v50, v0, 4, v162
	s_ashr_i32 s46, s41, 5
	s_ashr_i32 s47, s46, 31
	v_ashrrev_i32_e32 v51, 31, v50
	s_lshl_b64 s[46:47], s[46:47], 12
	v_lshl_add_u64 v[50:51], s[36:37], 0, v[50:51]
	v_lshl_add_u64 v[52:53], v[164:165], 0, s[46:47]
	v_mad_u64_u32 v[54:55], s[46:47], v50, s80, v[166:167]
	v_mad_i32_i24 v55, v51, s80, v55
	s_add_u32 m0, s98, 0x1000
	v_mad_i64_i32 v[232:233], s[100:101], v224, s99, v[54:55]
	v_add_u32_e32 v232, v228, v232
	global_load_lds_dwordx4 v[232:233], off
	s_add_u32 m0, s98, 0x1400
	v_mad_i64_i32 v[232:233], s[100:101], v225, s99, v[54:55]
	v_add_u32_e32 v232, v229, v232
	global_load_lds_dwordx4 v[232:233], off
	s_add_u32 m0, s98, 0x1800
	v_mad_i64_i32 v[232:233], s[100:101], v226, s99, v[54:55]
	v_add_u32_e32 v232, v228, v232
	global_load_lds_dwordx4 v[232:233], off
	s_add_u32 m0, s98, 0x1c00
	v_mad_i64_i32 v[232:233], s[100:101], v227, s99, v[54:55]
	v_add_u32_e32 v232, v229, v232
	global_load_lds_dwordx4 v[232:233], off
	global_load_dwordx4 v[126:129], v[52:53], off
	global_load_dwordx4 v[122:125], v[52:53], off offset:16
	global_load_dwordx4 v[118:121], v[52:53], off offset:2048
	global_load_dwordx4 v[114:117], v[52:53], off offset:2064
	s_waitcnt vmcnt(12)
	ds_read_b128 v[142:145], v234
	ds_read_b128 v[134:137], v235
	ds_read_b128 v[130:133], v236
	ds_read_b128 v[138:141], v237
	s_waitcnt lgkmcnt(3)
	v_mfma_f32_32x32x16_bf16 v[34:49], v[142:145], v[82:85], 0
	v_or_b32_e32 v0, s40, v175
	v_add_u32_e32 v50, 0xffffff7f, v0
	v_cmp_gt_u32_e32 vcc, s2, v50
	s_waitcnt lgkmcnt(2)
	v_mfma_f32_32x32x16_bf16 v[34:49], v[134:137], v[86:89], v[34:49]
	s_waitcnt lgkmcnt(1)
	v_mfma_f32_32x32x16_bf16 v[34:49], v[130:133], v[90:93], v[34:49]
	s_waitcnt lgkmcnt(0)
	v_mfma_f32_32x32x16_bf16 v[34:49], v[138:141], v[94:97], v[34:49]
	s_cbranch_vccz .LBB0_500
	v_sub_u32_e32 v0, v163, v0
	v_cmp_gt_u32_e32 vcc, s3, v0
	v_add_u32_e32 v50, 0xffffff80, v0
	s_nop 7
	v_cndmask_b32_e32 v34, v212, v34, vcc
	v_cmp_lt_u32_e32 vcc, s8, v50
	v_add_u32_e32 v50, 0xffffff81, v0
	s_nop 0
	v_cndmask_b32_e32 v35, v212, v35, vcc
	v_cmp_lt_u32_e32 vcc, s8, v50
	v_add_u32_e32 v50, 0xffffff82, v0
	s_nop 0
	v_cndmask_b32_e32 v36, v212, v36, vcc
	v_cmp_lt_u32_e32 vcc, s8, v50
	v_add_u32_e32 v50, 0xffffff87, v0
	s_nop 0
	v_cndmask_b32_e32 v37, v212, v37, vcc
	v_cmp_lt_u32_e32 vcc, s8, v50
	v_add_u32_e32 v50, 0xffffff88, v0
	s_nop 0
	v_cndmask_b32_e32 v38, v212, v38, vcc
	v_cmp_lt_u32_e32 vcc, s8, v50
	v_add_u32_e32 v50, 0xffffff89, v0
	s_nop 0
	v_cndmask_b32_e32 v39, v212, v39, vcc
	v_cmp_lt_u32_e32 vcc, s8, v50
	v_add_u32_e32 v50, 0xffffff8a, v0
	s_nop 0
	v_cndmask_b32_e32 v40, v212, v40, vcc
	v_cmp_lt_u32_e32 vcc, s8, v50
	v_add_u32_e32 v50, 0xffffff8f, v0
	s_nop 0
	v_cndmask_b32_e32 v41, v212, v41, vcc
	v_cmp_lt_u32_e32 vcc, s8, v50
	v_add_u32_e32 v50, 0xffffff90, v0
	s_nop 0
	v_cndmask_b32_e32 v42, v212, v42, vcc
	v_cmp_lt_u32_e32 vcc, s8, v50
	v_add_u32_e32 v50, 0xffffff91, v0
	s_nop 0
	v_cndmask_b32_e32 v43, v212, v43, vcc
	v_cmp_lt_u32_e32 vcc, s8, v50
	v_add_u32_e32 v50, 0xffffff92, v0
	s_nop 0
	v_cndmask_b32_e32 v44, v212, v44, vcc
	v_cmp_lt_u32_e32 vcc, s8, v50
	v_add_u32_e32 v50, 0xffffff97, v0
	s_nop 0
	v_cndmask_b32_e32 v45, v212, v45, vcc
	v_cmp_lt_u32_e32 vcc, s8, v50
	v_add_u32_e32 v50, 0xffffff98, v0
	s_nop 0
	v_cndmask_b32_e32 v46, v212, v46, vcc
	v_cmp_lt_u32_e32 vcc, s8, v50
	v_add_u32_e32 v50, 0xffffff99, v0
	v_add_u32_e32 v0, 0xffffff9a, v0
	v_cndmask_b32_e32 v47, v212, v47, vcc
	v_cmp_lt_u32_e32 vcc, s8, v50
	s_nop 1
	v_cndmask_b32_e32 v48, v212, v48, vcc
	v_cmp_lt_u32_e32 vcc, s8, v0
	s_nop 1
	v_cndmask_b32_e32 v49, v212, v49, vcc

.LBB0_508:
	s_cmp_lt_i32 s44, 0
	s_cselect_b64 s[38:39], -1, 0
	s_cmp_gt_i32 s44, -1
	s_cselect_b32 s41, s44, s45
	s_lshl_b32 s41, s41, 5
	s_sub_i32 s41, s30, s41
	v_or_b32_e32 v0, s41, v175
	v_lshl_add_u32 v2, v0, 4, v162
	s_ashr_i32 s46, s41, 5
	s_ashr_i32 s47, s46, 31
	v_ashrrev_i32_e32 v3, 31, v2
	s_lshl_b64 s[46:47], s[46:47], 12
	v_lshl_add_u64 v[2:3], s[36:37], 0, v[2:3]
	v_lshl_add_u64 v[4:5], v[164:165], 0, s[46:47]
	v_mad_u64_u32 v[6:7], s[46:47], v2, s80, v[166:167]
	v_mad_i32_i24 v7, v3, s80, v7
	s_add_u32 m0, s98, 0x0
	v_mad_i64_i32 v[232:233], s[100:101], v224, s99, v[6:7]
	v_add_u32_e32 v232, v228, v232
	global_load_lds_dwordx4 v[232:233], off
	s_add_u32 m0, s98, 0x400
	v_mad_i64_i32 v[232:233], s[100:101], v225, s99, v[6:7]
	v_add_u32_e32 v232, v229, v232
	global_load_lds_dwordx4 v[232:233], off
	s_add_u32 m0, s98, 0x800
	v_mad_i64_i32 v[232:233], s[100:101], v226, s99, v[6:7]
	v_add_u32_e32 v232, v228, v232
	global_load_lds_dwordx4 v[232:233], off
	s_add_u32 m0, s98, 0xc00
	v_mad_i64_i32 v[232:233], s[100:101], v227, s99, v[6:7]
	v_add_u32_e32 v232, v229, v232
	global_load_lds_dwordx4 v[232:233], off
	global_load_dwordx4 v[110:113], v[4:5], off
	global_load_dwordx4 v[106:109], v[4:5], off offset:16
	global_load_dwordx4 v[102:105], v[4:5], off offset:2048
	global_load_dwordx4 v[98:101], v[4:5], off offset:2064
	s_waitcnt vmcnt(12)
	ds_read_b128 v[66:69], v234 offset:4096
	ds_read_b128 v[154:157], v235 offset:4096
	ds_read_b128 v[150:153], v236 offset:4096
	ds_read_b128 v[146:149], v237 offset:4096
	s_waitcnt lgkmcnt(3)
	v_mfma_f32_32x32x16_bf16 v[66:81], v[66:69], v[82:85], 0
	v_or_b32_e32 v0, s40, v175
	v_add_u32_e32 v2, 0xffffff7f, v0
	v_cmp_gt_u32_e32 vcc, s2, v2
	s_waitcnt lgkmcnt(2)
	v_mfma_f32_32x32x16_bf16 v[66:81], v[154:157], v[86:89], v[66:81]
	s_waitcnt lgkmcnt(1)
	v_mfma_f32_32x32x16_bf16 v[66:81], v[150:153], v[90:93], v[66:81]
	s_waitcnt lgkmcnt(0)
	v_mfma_f32_32x32x16_bf16 v[66:81], v[146:149], v[94:97], v[66:81]
	s_cbranch_vccz .LBB0_510
	v_sub_u32_e32 v0, v163, v0
	v_cmp_gt_u32_e32 vcc, s3, v0
	v_add_u32_e32 v2, 0xffffff80, v0
	s_nop 7
	v_cndmask_b32_e32 v66, v212, v66, vcc
	v_cmp_lt_u32_e32 vcc, s8, v2
	v_add_u32_e32 v2, 0xffffff81, v0
	s_nop 0
	v_cndmask_b32_e32 v67, v212, v67, vcc
	v_cmp_lt_u32_e32 vcc, s8, v2
	v_add_u32_e32 v2, 0xffffff82, v0
	s_nop 0
	v_cndmask_b32_e32 v68, v212, v68, vcc
	v_cmp_lt_u32_e32 vcc, s8, v2
	v_add_u32_e32 v2, 0xffffff87, v0
	s_nop 0
	v_cndmask_b32_e32 v69, v212, v69, vcc
	v_cmp_lt_u32_e32 vcc, s8, v2
	v_add_u32_e32 v2, 0xffffff88, v0
	s_nop 0
	v_cndmask_b32_e32 v70, v212, v70, vcc
	v_cmp_lt_u32_e32 vcc, s8, v2
	v_add_u32_e32 v2, 0xffffff89, v0
	s_nop 0
	v_cndmask_b32_e32 v71, v212, v71, vcc
	v_cmp_lt_u32_e32 vcc, s8, v2
	v_add_u32_e32 v2, 0xffffff8a, v0
	s_nop 0
	v_cndmask_b32_e32 v72, v212, v72, vcc
	v_cmp_lt_u32_e32 vcc, s8, v2
	v_add_u32_e32 v2, 0xffffff8f, v0
	s_nop 0
	v_cndmask_b32_e32 v73, v212, v73, vcc
	v_cmp_lt_u32_e32 vcc, s8, v2
	v_add_u32_e32 v2, 0xffffff90, v0
	s_nop 0
	v_cndmask_b32_e32 v74, v212, v74, vcc
	v_cmp_lt_u32_e32 vcc, s8, v2
	v_add_u32_e32 v2, 0xffffff91, v0
	s_nop 0
	v_cndmask_b32_e32 v75, v212, v75, vcc
	v_cmp_lt_u32_e32 vcc, s8, v2
	v_add_u32_e32 v2, 0xffffff92, v0
	s_nop 0
	v_cndmask_b32_e32 v76, v212, v76, vcc
	v_cmp_lt_u32_e32 vcc, s8, v2
	v_add_u32_e32 v2, 0xffffff97, v0
	s_nop 0
	v_cndmask_b32_e32 v77, v212, v77, vcc
	v_cmp_lt_u32_e32 vcc, s8, v2
	v_add_u32_e32 v2, 0xffffff98, v0
	s_nop 0
	v_cndmask_b32_e32 v78, v212, v78, vcc
	v_cmp_lt_u32_e32 vcc, s8, v2
	v_add_u32_e32 v2, 0xffffff99, v0
	v_add_u32_e32 v0, 0xffffff9a, v0
	v_cndmask_b32_e32 v79, v212, v79, vcc
	v_cmp_lt_u32_e32 vcc, s8, v2
	s_nop 1
	v_cndmask_b32_e32 v80, v212, v80, vcc
	v_cmp_lt_u32_e32 vcc, s8, v0
	s_nop 1
	v_cndmask_b32_e32 v81, v212, v81, vcc

.LBB0_705:
	s_add_i32 s39, s40, 0x180
	s_lshr_b32 s43, s42, 2
	s_lshl_b32 s40, s44, 5
	s_add_i32 s40, s43, s40
	s_add_i32 s45, s40, 0xffffff80
	v_lshlrev_b32_e32 v36, 3, v34
	v_lshlrev_b32_e32 v30, 16, v0
	v_and_b32_e32 v31, 0xffff0000, v0
	v_or_b32_e32 v0, s45, v159
	v_or_b32_e32 v36, s39, v36
	s_ashr_i32 s39, s38, 31
	s_ashr_i32 s40, s45, 5
	v_lshl_add_u32 v38, v0, 2, v158
	s_ashr_i32 s41, s40, 31
	s_lshl_b64 s[38:39], s[38:39], 19
	v_ashrrev_i32_e32 v39, 31, v38
	s_lshl_b64 s[40:41], s[40:41], 12
	v_lshl_add_u64 v[170:171], v[160:161], 0, s[38:39]
	v_lshl_add_u64 v[38:39], s[0:1], 0, v[38:39]
	v_mov_b64_e32 v[42:43], s[66:67]
	v_lshl_add_u64 v[40:41], v[170:171], 0, s[40:41]
	v_mad_u64_u32 v[42:43], s[40:41], v38, s80, v[42:43]
	v_mov_b32_e32 v37, v1
	v_and_b32_e32 v35, 63, v2
	v_mad_i32_i24 v43, v39, s80, v43
	v_lshlrev_b64 v[36:37], 1, v[36:37]
	v_lshlrev_b32_e32 v0, 5, v35
	v_lshl_add_u64 v[38:39], v[42:43], 0, v[36:37]
	v_lshl_add_u64 v[40:41], v[40:41], 0, v[0:1]
	v_and_b32_e32 v238, 63, v199
	v_lshrrev_b32_e32 v239, 3, v238
	v_and_b32_e32 v240, 31, v238
	v_sub_u32_e32 v224, v239, v240
	v_add_u32_e32 v225, 8, v224
	v_add_u32_e32 v226, 16, v224
	v_add_u32_e32 v227, 24, v224
	v_lshrrev_b32_e32 v241, 5, v238
	v_and_b32_e32 v242, 7, v238
	v_lshrrev_b32_e32 v243, 4, v238
	v_xor_b32_e32 v228, v242, v243
	v_xor_b32_e32 v229, 4, v228
	v_sub_u32_e32 v228, v228, v241
	v_sub_u32_e32 v229, v229, v241
	v_lshlrev_b32_e32 v228, 4, v228
	v_lshlrev_b32_e32 v229, 4, v229
	v_lshrrev_b32_e32 v250, 6, v199
	v_lshlrev_b32_e32 v250, 13, v250
	v_bfe_u32 v251, v238, 1, 3
	v_xor_b32_e32 v251, v251, v241
	v_lshlrev_b32_e32 v251, 4, v251
	v_lshl_add_u32 v251, v240, 7, v251
	v_add_u32_e32 v234, v250, v251
	v_xor_b32_e32 v235, 0x20, v234
	v_xor_b32_e32 v236, 0x40, v234
	v_xor_b32_e32 v237, 0x60, v234
	v_readfirstlane_b32 s98, v250
	s_mov_b32 s99, 0x7000
	s_add_u32 m0, s98, 0x0
	v_mad_i64_i32 v[232:233], s[100:101], v224, s99, v[38:39]
	v_add_u32_e32 v232, v228, v232
	global_load_lds_dwordx4 v[232:233], off
	s_add_u32 m0, s98, 0x400
	v_mad_i64_i32 v[232:233], s[100:101], v225, s99, v[38:39]
	v_add_u32_e32 v232, v229, v232
	global_load_lds_dwordx4 v[232:233], off
	s_add_u32 m0, s98, 0x800
	v_mad_i64_i32 v[232:233], s[100:101], v226, s99, v[38:39]
	v_add_u32_e32 v232, v228, v232
	global_load_lds_dwordx4 v[232:233], off
	s_add_u32 m0, s98, 0xc00
	v_mad_i64_i32 v[232:233], s[100:101], v227, s99, v[38:39]
	v_add_u32_e32 v232, v229, v232
	global_load_lds_dwordx4 v[232:233], off
	global_load_dwordx4 v[110:113], v[40:41], off
	global_load_dwordx4 v[106:109], v[40:41], off offset:16
	global_load_dwordx4 v[102:105], v[40:41], off offset:2048
	global_load_dwordx4 v[98:101], v[40:41], off offset:2064
	v_readlane_b32 s12, v253, 2
	v_lshlrev_b32_e32 v167, 2, v34
	v_readlane_b32 s13, v253, 3
	v_readlane_b32 s23, v253, 13
	v_readlane_b32 s24, v253, 14
	v_readlane_b32 s25, v253, 15
	v_readlane_b32 s26, v253, 16
	v_readlane_b32 s27, v253, 17
	s_add_u32 s45, s12, s38
	v_lshlrev_b32_e32 v2, 16, v4
	v_and_b32_e32 v3, 0xffff0000, v4
	v_lshlrev_b32_e32 v4, 16, v5
	v_and_b32_e32 v5, 0xffff0000, v5
	v_lshlrev_b32_e32 v6, 16, v8
	v_and_b32_e32 v7, 0xffff0000, v8
	v_lshlrev_b32_e32 v8, 16, v9
	v_and_b32_e32 v9, 0xffff0000, v9
	v_lshlrev_b32_e32 v10, 16, v12
	v_and_b32_e32 v11, 0xffff0000, v12
	v_lshlrev_b32_e32 v12, 16, v13
	v_and_b32_e32 v13, 0xffff0000, v13
	v_lshlrev_b32_e32 v14, 16, v16
	v_and_b32_e32 v15, 0xffff0000, v16
	v_lshlrev_b32_e32 v16, 16, v17
	v_and_b32_e32 v17, 0xffff0000, v17
	v_lshlrev_b32_e32 v18, 16, v20
	v_and_b32_e32 v19, 0xffff0000, v20
	v_lshlrev_b32_e32 v20, 16, v21
	v_and_b32_e32 v21, 0xffff0000, v21
	v_lshlrev_b32_e32 v22, 16, v24
	v_and_b32_e32 v23, 0xffff0000, v24
	v_lshlrev_b32_e32 v24, 16, v25
	v_and_b32_e32 v25, 0xffff0000, v25
	v_lshlrev_b32_e32 v26, 16, v28
	v_and_b32_e32 v27, 0xffff0000, v28
	v_lshlrev_b32_e32 v28, 16, v29
	v_and_b32_e32 v29, 0xffff0000, v29
	v_lshlrev_b32_e32 v32, 16, v33
	v_and_b32_e32 v33, 0xffff0000, v33
	v_lshlrev_b32_e32 v172, 4, v35
	v_or_b32_e32 v173, 0x80, v167
	v_lshl_add_u64 v[174:175], s[66:67], 0, v[36:37]
	v_or_b32_e32 v178, s43, v159
	s_addc_u32 s46, s13, s39
	s_mov_b32 s23, 0x800000
	s_movk_i32 s24, 0xf00
	s_movk_i32 s25, 0x104
	s_mov_b64 s[26:27], 0x400c0
	v_readlane_b32 s14, v253, 4
	v_readlane_b32 s15, v253, 5
	v_readlane_b32 s16, v253, 6
	v_readlane_b32 s17, v253, 7
	v_readlane_b32 s18, v253, 8
	v_readlane_b32 s19, v253, 9
	v_readlane_b32 s20, v253, 10
	v_readlane_b32 s21, v253, 11
	v_readlane_b32 s22, v253, 12
	s_branch .LBB0_709

.LBB0_713:
	s_cmp_gt_i32 s47, -1
	s_cselect_b64 s[38:39], -1, 0
	s_cmp_lt_i32 s47, 0
	s_cselect_b32 s41, s44, s47
	s_cmp_lt_i32 s41, 5
	s_cselect_b64 vcc, -1, 0
	s_movk_i32 s99, 0x1c00
	s_cselect_b32 s99, 0x7000, s99
	s_and_b64 s[48:49], vcc, exec
	s_cselect_b32 s48, 0xffffff80, s83
	s_cselect_b32 s49, s43, s42
	s_lshl_b32 s41, s41, 5
	s_add_i32 s41, s48, s41
	v_mov_b32_e32 v0, s46
	s_add_i32 s41, s41, s49
	v_cndmask_b32_e32 v35, v0, v171, vcc
	v_or_b32_e32 v0, s41, v159
	v_lshl_add_u32 v36, v0, 2, v158
	s_ashr_i32 s48, s41, 5
	v_cndmask_b32_e32 v36, v0, v36, vcc
	s_ashr_i32 s49, s48, 31
	v_mov_b32_e32 v34, s45
	v_ashrrev_i32_e32 v37, 31, v36
	v_cndmask_b32_e32 v34, v34, v170, vcc
	s_lshl_b64 s[48:49], s[48:49], 12
	v_lshl_add_u64 v[52:53], s[0:1], 0, v[36:37]
	v_lshl_add_u64 v[34:35], v[34:35], 0, s[48:49]
	v_mad_u64_u32 v[54:55], s[48:49], v52, s80, v[174:175]
	v_lshlrev_b32_e32 v0, 1, v172
	v_mad_i32_i24 v55, v53, s80, v55
	v_lshl_add_u64 v[50:51], v[34:35], 0, v[0:1]
	s_add_u32 m0, s98, 0x1000
	v_mad_i64_i32 v[232:233], s[100:101], v224, s99, v[54:55]
	v_add_u32_e32 v232, v228, v232
	global_load_lds_dwordx4 v[232:233], off
	s_add_u32 m0, s98, 0x1400
	v_mad_i64_i32 v[232:233], s[100:101], v225, s99, v[54:55]
	v_add_u32_e32 v232, v229, v232
	global_load_lds_dwordx4 v[232:233], off
	s_add_u32 m0, s98, 0x1800
	v_mad_i64_i32 v[232:233], s[100:101], v226, s99, v[54:55]
	v_add_u32_e32 v232, v228, v232
	global_load_lds_dwordx4 v[232:233], off
	s_add_u32 m0, s98, 0x1c00
	v_mad_i64_i32 v[232:233], s[100:101], v227, s99, v[54:55]
	v_add_u32_e32 v232, v229, v232
	global_load_lds_dwordx4 v[232:233], off
	global_load_dwordx4 v[130:133], v[50:51], off
	global_load_dwordx4 v[122:125], v[50:51], off offset:16
	global_load_dwordx4 v[118:121], v[50:51], off offset:2048
	global_load_dwordx4 v[114:117], v[50:51], off offset:2064
	s_waitcnt vmcnt(12)
	ds_read_b128 v[142:145], v234
	ds_read_b128 v[134:137], v235
	ds_read_b128 v[126:129], v236
	ds_read_b128 v[138:141], v237
	s_waitcnt lgkmcnt(3)
	v_mfma_f32_32x32x16_bf16 v[34:49], v[142:145], v[82:85], 0
	s_cmp_lt_u32 s44, 5
	s_cselect_b64 vcc, -1, 0
	s_and_b64 s[48:49], vcc, exec
	v_cndmask_b32_e32 v50, v166, v178, vcc
	s_cselect_b32 s41, 0x80, s58
	s_cselect_b32 s44, s43, s42
	v_add_u32_e32 v50, s41, v50
	s_waitcnt lgkmcnt(2)
	v_mfma_f32_32x32x16_bf16 v[34:49], v[134:137], v[86:89], v[34:49]
	s_add_i32 s40, s40, s44
	v_subrev_u32_e32 v50, s40, v50
	v_add_u32_e32 v51, 0xffffff7f, v50
	v_cmp_gt_u32_e32 vcc, s2, v51
	s_waitcnt lgkmcnt(1)
	v_mfma_f32_32x32x16_bf16 v[34:49], v[126:129], v[90:93], v[34:49]
	s_waitcnt lgkmcnt(0)
	v_mfma_f32_32x32x16_bf16 v[34:49], v[138:141], v[94:97], v[34:49]
	s_cbranch_vccz .LBB0_715
	v_sub_u32_e32 v50, v173, v50
	v_cmp_gt_u32_e32 vcc, s3, v50
	v_add_u32_e32 v51, 0xffffff80, v50
	s_nop 7
	v_cndmask_b32_e32 v34, v212, v34, vcc
	v_cmp_lt_u32_e32 vcc, s8, v51
	v_add_u32_e32 v51, 0xffffff81, v50
	s_nop 0
	v_cndmask_b32_e32 v35, v212, v35, vcc
	v_cmp_lt_u32_e32 vcc, s8, v51
	v_add_u32_e32 v51, 0xffffff82, v50
	s_nop 0
	v_cndmask_b32_e32 v36, v212, v36, vcc
	v_cmp_lt_u32_e32 vcc, s8, v51
	v_add_u32_e32 v51, 0xffffff87, v50
	s_nop 0
	v_cndmask_b32_e32 v37, v212, v37, vcc
	v_cmp_lt_u32_e32 vcc, s8, v51
	v_add_u32_e32 v51, 0xffffff88, v50
	s_nop 0
	v_cndmask_b32_e32 v38, v212, v38, vcc
	v_cmp_lt_u32_e32 vcc, s8, v51
	v_add_u32_e32 v51, 0xffffff89, v50
	s_nop 0
	v_cndmask_b32_e32 v39, v212, v39, vcc
	v_cmp_lt_u32_e32 vcc, s8, v51
	v_add_u32_e32 v51, 0xffffff8a, v50
	s_nop 0
	v_cndmask_b32_e32 v40, v212, v40, vcc
	v_cmp_lt_u32_e32 vcc, s8, v51
	v_add_u32_e32 v51, 0xffffff8f, v50
	s_nop 0
	v_cndmask_b32_e32 v41, v212, v41, vcc
	v_cmp_lt_u32_e32 vcc, s8, v51
	v_add_u32_e32 v51, 0xffffff90, v50
	s_nop 0
	v_cndmask_b32_e32 v42, v212, v42, vcc
	v_cmp_lt_u32_e32 vcc, s8, v51
	v_add_u32_e32 v51, 0xffffff91, v50
	s_nop 0
	v_cndmask_b32_e32 v43, v212, v43, vcc
	v_cmp_lt_u32_e32 vcc, s8, v51
	v_add_u32_e32 v51, 0xffffff92, v50
	s_nop 0
	v_cndmask_b32_e32 v44, v212, v44, vcc
	v_cmp_lt_u32_e32 vcc, s8, v51
	v_add_u32_e32 v51, 0xffffff97, v50
	s_nop 0
	v_cndmask_b32_e32 v45, v212, v45, vcc
	v_cmp_lt_u32_e32 vcc, s8, v51
	v_add_u32_e32 v51, 0xffffff98, v50
	s_nop 0
	v_cndmask_b32_e32 v46, v212, v46, vcc
	v_cmp_lt_u32_e32 vcc, s8, v51
	v_add_u32_e32 v51, 0xffffff99, v50
	v_add_u32_e32 v50, 0xffffff9a, v50
	v_cndmask_b32_e32 v47, v212, v47, vcc
	v_cmp_lt_u32_e32 vcc, s8, v51
	s_nop 1
	v_cndmask_b32_e32 v48, v212, v48, vcc
	v_cmp_lt_u32_e32 vcc, s8, v50
	s_nop 1
	v_cndmask_b32_e32 v49, v212, v49, vcc

.LBB0_722:
	s_cmp_lt_i32 s44, 0
	s_cselect_b64 s[38:39], -1, 0
	s_cmp_gt_i32 s44, -1
	s_cselect_b32 s41, s44, s47
	s_cmp_lt_i32 s41, 5
	s_cselect_b64 vcc, -1, 0
	s_movk_i32 s99, 0x1c00
	s_cselect_b32 s99, 0x7000, s99
	s_and_b64 s[48:49], vcc, exec
	s_cselect_b32 s48, 0xffffff80, s83
	s_cselect_b32 s49, s43, s42
	s_lshl_b32 s41, s41, 5
	s_add_i32 s41, s48, s41
	s_add_i32 s41, s41, s49
	v_or_b32_e32 v4, s41, v159
	v_lshl_add_u32 v5, v4, 2, v158
	v_mov_b32_e32 v2, s46
	s_ashr_i32 s48, s41, 5
	v_cndmask_b32_e32 v4, v4, v5, vcc
	v_cndmask_b32_e32 v3, v2, v171, vcc
	s_ashr_i32 s49, s48, 31
	v_mov_b32_e32 v2, s45
	v_ashrrev_i32_e32 v5, 31, v4
	v_cndmask_b32_e32 v2, v2, v170, vcc
	s_lshl_b64 s[48:49], s[48:49], 12
	v_lshl_add_u64 v[4:5], s[0:1], 0, v[4:5]
	v_lshl_add_u64 v[2:3], v[2:3], 0, s[48:49]
	v_mad_u64_u32 v[6:7], s[48:49], v4, s80, v[174:175]
	v_mad_i32_i24 v7, v5, s80, v7
	v_lshl_add_u64 v[2:3], v[2:3], 0, v[0:1]
	s_add_u32 m0, s98, 0x0
	v_mad_i64_i32 v[232:233], s[100:101], v224, s99, v[6:7]
	v_add_u32_e32 v232, v228, v232
	global_load_lds_dwordx4 v[232:233], off
	s_add_u32 m0, s98, 0x400
	v_mad_i64_i32 v[232:233], s[100:101], v225, s99, v[6:7]
	v_add_u32_e32 v232, v229, v232
	global_load_lds_dwordx4 v[232:233], off
	s_add_u32 m0, s98, 0x800
	v_mad_i64_i32 v[232:233], s[100:101], v226, s99, v[6:7]
	v_add_u32_e32 v232, v228, v232
	global_load_lds_dwordx4 v[232:233], off
	s_add_u32 m0, s98, 0xc00
	v_mad_i64_i32 v[232:233], s[100:101], v227, s99, v[6:7]
	v_add_u32_e32 v232, v229, v232
	global_load_lds_dwordx4 v[232:233], off
	global_load_dwordx4 v[110:113], v[2:3], off
	global_load_dwordx4 v[106:109], v[2:3], off offset:16
	global_load_dwordx4 v[102:105], v[2:3], off offset:2048
	global_load_dwordx4 v[98:101], v[2:3], off offset:2064
	s_waitcnt vmcnt(12)
	ds_read_b128 v[66:69], v234 offset:4096
	ds_read_b128 v[154:157], v235 offset:4096
	ds_read_b128 v[150:153], v236 offset:4096
	ds_read_b128 v[146:149], v237 offset:4096
	s_waitcnt lgkmcnt(3)
	v_mfma_f32_32x32x16_bf16 v[66:81], v[66:69], v[82:85], 0
	s_cmp_lt_u32 s47, 5
	s_cselect_b64 vcc, -1, 0
	s_and_b64 s[48:49], vcc, exec
	v_cndmask_b32_e32 v0, v166, v178, vcc
	s_cselect_b32 s41, 0x80, s58
	s_cselect_b32 s47, s43, s42
	v_add_u32_e32 v0, s41, v0
	s_waitcnt lgkmcnt(2)
	v_mfma_f32_32x32x16_bf16 v[66:81], v[154:157], v[86:89], v[66:81]
	s_add_i32 s40, s40, s47
	v_subrev_u32_e32 v0, s40, v0
	v_add_u32_e32 v2, 0xffffff7f, v0
	v_cmp_gt_u32_e32 vcc, s2, v2
	s_waitcnt lgkmcnt(1)
	v_mfma_f32_32x32x16_bf16 v[66:81], v[150:153], v[90:93], v[66:81]
	s_waitcnt lgkmcnt(0)
	v_mfma_f32_32x32x16_bf16 v[66:81], v[146:149], v[94:97], v[66:81]
	s_cbranch_vccz .LBB0_724
	v_sub_u32_e32 v0, v173, v0
	v_cmp_gt_u32_e32 vcc, s3, v0
	v_add_u32_e32 v2, 0xffffff80, v0
	s_nop 7
	v_cndmask_b32_e32 v66, v212, v66, vcc
	v_cmp_lt_u32_e32 vcc, s8, v2
	v_add_u32_e32 v2, 0xffffff81, v0
	s_nop 0
	v_cndmask_b32_e32 v67, v212, v67, vcc
	v_cmp_lt_u32_e32 vcc, s8, v2
	v_add_u32_e32 v2, 0xffffff82, v0
	s_nop 0
	v_cndmask_b32_e32 v68, v212, v68, vcc
	v_cmp_lt_u32_e32 vcc, s8, v2
	v_add_u32_e32 v2, 0xffffff87, v0
	s_nop 0
	v_cndmask_b32_e32 v69, v212, v69, vcc
	v_cmp_lt_u32_e32 vcc, s8, v2
	v_add_u32_e32 v2, 0xffffff88, v0
	s_nop 0
	v_cndmask_b32_e32 v70, v212, v70, vcc
	v_cmp_lt_u32_e32 vcc, s8, v2
	v_add_u32_e32 v2, 0xffffff89, v0
	s_nop 0
	v_cndmask_b32_e32 v71, v212, v71, vcc
	v_cmp_lt_u32_e32 vcc, s8, v2
	v_add_u32_e32 v2, 0xffffff8a, v0
	s_nop 0
	v_cndmask_b32_e32 v72, v212, v72, vcc
	v_cmp_lt_u32_e32 vcc, s8, v2
	v_add_u32_e32 v2, 0xffffff8f, v0
	s_nop 0
	v_cndmask_b32_e32 v73, v212, v73, vcc
	v_cmp_lt_u32_e32 vcc, s8, v2
	v_add_u32_e32 v2, 0xffffff90, v0
	s_nop 0
	v_cndmask_b32_e32 v74, v212, v74, vcc
	v_cmp_lt_u32_e32 vcc, s8, v2
	v_add_u32_e32 v2, 0xffffff91, v0
	s_nop 0
	v_cndmask_b32_e32 v75, v212, v75, vcc
	v_cmp_lt_u32_e32 vcc, s8, v2
	v_add_u32_e32 v2, 0xffffff92, v0
	s_nop 0
	v_cndmask_b32_e32 v76, v212, v76, vcc
	v_cmp_lt_u32_e32 vcc, s8, v2
	v_add_u32_e32 v2, 0xffffff97, v0
	s_nop 0
	v_cndmask_b32_e32 v77, v212, v77, vcc
	v_cmp_lt_u32_e32 vcc, s8, v2
	v_add_u32_e32 v2, 0xffffff98, v0
	s_nop 0
	v_cndmask_b32_e32 v78, v212, v78, vcc
	v_cmp_lt_u32_e32 vcc, s8, v2
	v_add_u32_e32 v2, 0xffffff99, v0
	v_add_u32_e32 v0, 0xffffff9a, v0
	v_cndmask_b32_e32 v79, v212, v79, vcc
	v_cmp_lt_u32_e32 vcc, s8, v2
	s_nop 1
	v_cndmask_b32_e32 v80, v212, v80, vcc
	v_cmp_lt_u32_e32 vcc, s8, v0
	s_nop 1
	v_cndmask_b32_e32 v81, v212, v81, vcc

.LBB0_759:
	s_or_b64 exec, exec, s[40:41]
	v_ashrrev_i32_e32 v165, 31, v164
	v_readlane_b32 s48, v252, 0
	v_ashrrev_i32_e32 v167, 31, v166
	v_lshlrev_b64 v[2:3], 17, v[164:165]
	v_readlane_b32 s49, v252, 1
	v_mov_b32_e32 v0, v199
	v_lshlrev_b64 v[4:5], 13, v[166:167]
	v_lshl_add_u64 v[2:3], s[48:49], 0, v[2:3]
	v_lshl_add_u64 v[2:3], v[2:3], 0, v[4:5]
	v_lshlrev_b32_e32 v4, 5, v192
	v_and_or_b32 v0, v0, 31, v4
	s_waitcnt vmcnt(0)
	v_add_u32_e32 v4, -1, v193
	v_min_i32_e32 v4, v0, v4
	v_ashrrev_i32_e32 v5, 31, v4
	v_lshl_add_u64 v[2:3], v[4:5], 1, v[2:3]
	v_ashrrev_i32_e32 v159, 31, v158
	v_readlane_b32 s12, v252, 8
	global_load_ushort v165, v[2:3], off
	v_lshlrev_b64 v[2:3], 13, v[158:159]
	v_readlane_b32 s18, v252, 14
	v_readlane_b32 s19, v252, 15
	v_mov_b32_e32 v163, v1
	v_mov_b32_e32 v0, v199
	v_lshl_add_u64 v[2:3], s[18:19], 0, v[2:3]
	v_lshl_add_u64 v[2:3], v[162:163], 1, v[2:3]
	global_load_ushort v200, v[2:3], off
	v_ashrrev_i32_e32 v2, 2, v158
	v_ashrrev_i32_e32 v3, 31, v2
	v_lshlrev_b64 v[174:175], 12, v[2:3]
	s_and_b64 s[0:1], exec, vcc
	v_lshl_add_u64 v[172:173], v[174:175], 0, v[162:163]
	s_movk_i32 s12, 0xe00
	s_or_b64 s[44:45], s[0:1], s[44:45]
	v_mad_u64_u32 v[2:3], s[0:1], v172, s12, 0
	v_lshrrev_b32_e32 v4, 2, v0
	v_mad_i32_i24 v3, v173, s12, v3
	v_and_b32_e32 v4, 8, v4
	v_and_b32_e32 v167, 3, v158
	v_and_b32_e32 v201, 31, v0
	v_and_b32_e32 v163, 63, v0
	v_cmp_lt_i32_e32 vcc, -1, v160
	v_mov_b32_e32 v183, 0xc61c4000
	v_mov_b32_e32 v71, 0
	v_lshl_add_u64 v[170:171], v[2:3], 1, s[66:67]
	v_lshlrev_b32_e32 v168, 1, v4
	v_mov_b32_e32 v49, 0
	v_mov_b32_e32 v48, 0
	v_mov_b32_e32 v47, 0
	v_mov_b32_e32 v46, 0
	v_mov_b32_e32 v45, 0
	v_mov_b32_e32 v44, 0
	v_mov_b32_e32 v43, 0
	v_mov_b32_e32 v42, 0
	v_mov_b32_e32 v41, 0
	v_mov_b32_e32 v40, 0
	v_mov_b32_e32 v39, 0
	v_mov_b32_e32 v38, 0
	v_mov_b32_e32 v37, 0
	v_mov_b32_e32 v36, 0
	v_mov_b32_e32 v35, 0
	v_mov_b32_e32 v34, 0
	v_mov_b32_e32 v65, 0
	v_mov_b32_e32 v64, 0
	v_mov_b32_e32 v63, 0
	v_mov_b32_e32 v62, 0
	v_mov_b32_e32 v61, 0
	v_mov_b32_e32 v60, 0
	v_mov_b32_e32 v59, 0
	v_mov_b32_e32 v58, 0
	v_mov_b32_e32 v57, 0
	v_mov_b32_e32 v56, 0
	v_mov_b32_e32 v55, 0
	v_mov_b32_e32 v54, 0
	v_mov_b32_e32 v53, 0
	v_mov_b32_e32 v52, 0
	v_mov_b32_e32 v51, 0
	v_mov_b32_e32 v50, 0
	v_readlane_b32 s50, v252, 2
	v_readlane_b32 s51, v252, 3
	v_readlane_b32 s52, v252, 4
	v_readlane_b32 s53, v252, 5
	v_readlane_b32 s54, v252, 6
	v_readlane_b32 s55, v252, 7
	v_readlane_b32 s13, v252, 9
	v_readlane_b32 s14, v252, 10
	v_readlane_b32 s15, v252, 11
	v_readlane_b32 s16, v252, 12
	v_readlane_b32 s17, v252, 13
	s_and_saveexec_b64 s[0:1], vcc
	s_cbranch_execz .LBB0_775
	v_readlane_b32 s12, v253, 2
	v_lshlrev_b64 v[2:3], 19, v[158:159]
	v_readlane_b32 s22, v253, 12
	v_readlane_b32 s23, v253, 13
	v_lshlrev_b32_e32 v0, 5, v163
	v_readlane_b32 s13, v253, 3
	v_lshl_add_u64 v[2:3], s[22:23], 0, v[2:3]
	v_lshl_add_u64 v[176:177], v[2:3], 0, v[0:1]
	v_lshlrev_b32_e32 v0, 7, v167
	v_lshl_add_u64 v[4:5], v[170:171], 0, v[0:1]
	v_mov_b32_e32 v169, v1
	v_lshl_add_u64 v[4:5], v[4:5], 0, v[168:169]
	s_mov_b64 s[12:13], 0x1300
	v_lshl_add_u64 v[6:7], v[4:5], 0, s[12:13]
	v_add_co_u32_e32 v4, vcc, s97, v4
	global_load_dwordx4 v[82:85], v[6:7], off offset:64
	global_load_dwordx4 v[86:89], v[6:7], off offset:32
	v_addc_co_u32_e32 v5, vcc, 0, v5, vcc
	global_load_dwordx4 v[90:93], v[6:7], off offset:96
	global_load_dwordx4 v[94:97], v[4:5], off offset:768
	v_or_b32_e32 v6, v0, v168
	v_lshlrev_b32_e32 v0, 8, v160
	v_lshl_add_u64 v[4:5], v[174:175], 0, v[0:1]
	v_mov_b64_e32 v[2:3], s[66:67]
	v_or_b32_e32 v0, v4, v201
	v_mad_u64_u32 v[2:3], s[40:41], v0, s80, v[2:3]
	v_lshlrev_b32_e32 v184, 3, v160
	v_mad_i32_i24 v3, v5, s80, v3
	v_add_u32_e32 v0, 0x1500, v6
	v_mov_b32_e32 v185, v1
	v_lshl_add_u64 v[2:3], v[2:3], 0, v[0:1]
	v_lshlrev_b64 v[4:5], 12, v[184:185]
	v_lshl_add_u64 v[4:5], v[176:177], 0, v[4:5]
	v_and_b32_e32 v238, 63, v199
	v_lshrrev_b32_e32 v239, 3, v238
	v_and_b32_e32 v240, 31, v238
	v_sub_u32_e32 v224, v239, v240
	v_add_u32_e32 v225, 8, v224
	v_add_u32_e32 v226, 16, v224
	v_add_u32_e32 v227, 24, v224
	v_lshrrev_b32_e32 v241, 5, v238
	v_and_b32_e32 v242, 7, v238
	v_lshrrev_b32_e32 v243, 4, v238
	v_xor_b32_e32 v228, v242, v243
	v_xor_b32_e32 v229, 4, v228
	v_sub_u32_e32 v228, v228, v241
	v_sub_u32_e32 v229, v229, v241
	v_lshlrev_b32_e32 v228, 4, v228
	v_lshlrev_b32_e32 v229, 4, v229
	v_lshrrev_b32_e32 v250, 6, v199
	v_lshlrev_b32_e32 v250, 13, v250
	v_bfe_u32 v251, v238, 1, 3
	v_xor_b32_e32 v251, v251, v241
	v_lshlrev_b32_e32 v251, 4, v251
	v_lshl_add_u32 v251, v240, 7, v251
	v_add_u32_e32 v234, v250, v251
	v_xor_b32_e32 v235, 0x20, v234
	v_xor_b32_e32 v236, 0x40, v234
	v_xor_b32_e32 v237, 0x60, v234
	v_readfirstlane_b32 s98, v250
	s_mov_b32 s99, 0x1c00
	s_add_u32 m0, s98, 0x0
	v_mad_i64_i32 v[232:233], s[100:101], v224, s99, v[2:3]
	v_add_u32_e32 v232, v228, v232
	global_load_lds_dwordx4 v[232:233], off
	s_add_u32 m0, s98, 0x400
	v_mad_i64_i32 v[232:233], s[100:101], v225, s99, v[2:3]
	v_add_u32_e32 v232, v229, v232
	global_load_lds_dwordx4 v[232:233], off
	s_add_u32 m0, s98, 0x800
	v_mad_i64_i32 v[232:233], s[100:101], v226, s99, v[2:3]
	v_add_u32_e32 v232, v228, v232
	global_load_lds_dwordx4 v[232:233], off
	s_add_u32 m0, s98, 0xc00
	v_mad_i64_i32 v[232:233], s[100:101], v227, s99, v[2:3]
	v_add_u32_e32 v232, v229, v232
	global_load_lds_dwordx4 v[232:233], off
	global_load_dwordx4 v[110:113], v[4:5], off
	global_load_dwordx4 v[106:109], v[4:5], off offset:16
	global_load_dwordx4 v[102:105], v[4:5], off offset:2048
	global_load_dwordx4 v[98:101], v[4:5], off offset:2064
	v_mov_b32_e32 v2, v1
	v_mov_b32_e32 v3, v1
	v_mov_b32_e32 v4, v1
	v_mov_b32_e32 v5, v1
	v_mov_b32_e32 v6, v1
	v_mov_b32_e32 v7, v1
	v_mov_b32_e32 v8, v1
	v_mov_b32_e32 v9, v1
	v_mov_b32_e32 v10, v1
	v_mov_b32_e32 v11, v1
	v_mov_b32_e32 v12, v1
	v_mov_b32_e32 v13, v1
	v_mov_b32_e32 v14, v1
	v_mov_b32_e32 v15, v1
	v_mov_b32_e32 v16, v1
	v_mov_b32_e32 v17, v1
	v_mov_b32_e32 v18, v1
	v_mov_b32_e32 v19, v1
	v_mov_b32_e32 v20, v1
	v_mov_b32_e32 v21, v1
	v_mov_b32_e32 v22, v1
	v_mov_b32_e32 v23, v1
	v_mov_b32_e32 v24, v1
	v_mov_b32_e32 v25, v1
	v_mov_b32_e32 v26, v1
	v_mov_b32_e32 v27, v1
	v_mov_b32_e32 v28, v1
	v_mov_b32_e32 v29, v1
	v_mov_b32_e32 v30, v1
	v_mov_b32_e32 v31, v1
	v_lshl_add_u64 v[178:179], s[66:67], 0, v[0:1]
	v_mov_b32_e32 v0, v1
	v_mov_b64_e32 v[32:33], v[30:31]
	v_or_b32_e32 v159, 7, v184
	v_or_b32_e32 v174, v174, v201
	v_mov_b32_e32 v183, 0xc61c4000
	v_mov_b32_e32 v71, 0
	s_mov_b64 s[46:47], 0
	v_mov_b64_e32 v[30:31], v[28:29]
	v_mov_b64_e32 v[28:29], v[26:27]
	v_mov_b64_e32 v[26:27], v[24:25]
	v_mov_b64_e32 v[24:25], v[22:23]
	v_mov_b64_e32 v[22:23], v[20:21]
	v_mov_b64_e32 v[20:21], v[18:19]
	v_mov_b64_e32 v[18:19], v[16:17]
	v_mov_b64_e32 v[16:17], v[14:15]
	v_mov_b64_e32 v[14:15], v[12:13]
	v_mov_b64_e32 v[12:13], v[10:11]
	v_mov_b64_e32 v[10:11], v[8:9]
	v_mov_b64_e32 v[8:9], v[6:7]
	v_mov_b64_e32 v[6:7], v[4:5]
	v_mov_b64_e32 v[4:5], v[2:3]
	v_mov_b64_e32 v[2:3], v[0:1]
	v_readlane_b32 s14, v253, 4
	v_readlane_b32 s15, v253, 5
	v_readlane_b32 s16, v253, 6
	v_readlane_b32 s17, v253, 7
	v_readlane_b32 s18, v253, 8
	v_readlane_b32 s19, v253, 9
	v_readlane_b32 s20, v253, 10
	v_readlane_b32 s21, v253, 11
	v_readlane_b32 s24, v253, 14
	v_readlane_b32 s25, v253, 15
	v_readlane_b32 s26, v253, 16
	v_readlane_b32 s27, v253, 17
	s_branch .LBB0_764

.LBB0_764:
	v_add_u32_e32 v0, 1, v184
	v_cmp_lt_i32_e32 vcc, v184, v159
	s_nop 1
	v_cndmask_b32_e32 v182, -1, v0, vcc
	v_cmp_gt_i32_e32 vcc, 0, v182
	s_nop 1
	v_cndmask_b32_e32 v50, v182, v184, vcc
	v_lshlrev_b32_e32 v34, 5, v50
	v_ashrrev_i32_e32 v35, 31, v34
	v_lshl_add_u64 v[52:53], v[174:175], 0, v[34:35]
	v_mad_u64_u32 v[54:55], s[40:41], v52, s80, v[178:179]
	v_mov_b32_e32 v0, v55
	v_mad_u64_u32 v[52:53], s[40:41], v53, s80, v[0:1]
	v_ashrrev_i32_e32 v51, 31, v50
	v_mov_b32_e32 v55, v52
	v_lshlrev_b64 v[50:51], 12, v[50:51]
	v_lshl_add_u64 v[50:51], v[176:177], 0, v[50:51]
	s_add_u32 m0, s98, 0x1000
	v_mad_i64_i32 v[232:233], s[100:101], v224, s99, v[54:55]
	v_add_u32_e32 v232, v228, v232
	global_load_lds_dwordx4 v[232:233], off
	s_add_u32 m0, s98, 0x1400
	v_mad_i64_i32 v[232:233], s[100:101], v225, s99, v[54:55]
	v_add_u32_e32 v232, v229, v232
	global_load_lds_dwordx4 v[232:233], off
	s_add_u32 m0, s98, 0x1800
	v_mad_i64_i32 v[232:233], s[100:101], v226, s99, v[54:55]
	v_add_u32_e32 v232, v228, v232
	global_load_lds_dwordx4 v[232:233], off
	s_add_u32 m0, s98, 0x1c00
	v_mad_i64_i32 v[232:233], s[100:101], v227, s99, v[54:55]
	v_add_u32_e32 v232, v229, v232
	global_load_lds_dwordx4 v[232:233], off
	global_load_dwordx4 v[126:129], v[50:51], off
	global_load_dwordx4 v[122:125], v[50:51], off offset:16
	global_load_dwordx4 v[118:121], v[50:51], off offset:2048
	global_load_dwordx4 v[114:117], v[50:51], off offset:2064
	s_waitcnt vmcnt(12)
	ds_read_b128 v[142:145], v234
	ds_read_b128 v[134:137], v235
	ds_read_b128 v[130:133], v236
	ds_read_b128 v[138:141], v237
	s_waitcnt lgkmcnt(3)
	v_mfma_f32_32x32x16_bf16 v[34:49], v[142:145], v[94:97], 0
	v_cmp_lt_i32_e64 s[40:41], -1, v182
	s_waitcnt lgkmcnt(2)
	v_mfma_f32_32x32x16_bf16 v[34:49], v[134:137], v[86:89], v[34:49]
	s_waitcnt lgkmcnt(1)
	v_mfma_f32_32x32x16_bf16 v[34:49], v[130:133], v[82:85], v[34:49]
	s_waitcnt lgkmcnt(0)
	v_mfma_f32_32x32x16_bf16 v[34:49], v[138:141], v[90:93], v[34:49]
	s_nop 11
	v_max_f32_e32 v0, v37, v37
	v_max_f32_e32 v50, v36, v36
	v_max_f32_e32 v0, v50, v0
	v_max_f32_e32 v50, v41, v41
	v_max_f32_e32 v51, v40, v40
	v_max_f32_e32 v50, v51, v50
	v_max_f32_e32 v51, v43, v43
	v_max_f32_e32 v52, v42, v42
	v_max_f32_e32 v51, v52, v51
	v_max_f32_e32 v52, v45, v45
	v_max_f32_e32 v53, v44, v44
	v_max_f32_e32 v52, v53, v52
	v_max_f32_e32 v53, v49, v49
	v_max_f32_e32 v54, v48, v48
	v_max_f32_e32 v53, v54, v53
	v_max3_f32 v53, v46, v47, v53
	v_max3_f32 v0, v34, v35, v0
	v_max3_f32 v50, v38, v39, v50
	v_max3_f32 v51, v51, v52, v53
	v_max3_f32 v0, v0, v50, v51
	v_mov_b32_e32 v50, v0
	s_nop 1
	v_permlane32_swap_b32_e32 v0, v50
	v_max_f32_e32 v50, v50, v50
	v_max_f32_e32 v0, v0, v0
	v_max_f32_e32 v0, v0, v50
	v_add_f32_e32 v50, 0x41800000, v183
	v_cmp_gt_f32_e32 vcc, v0, v50
	s_cbranch_vccz .LBB0_766
	s_nop 0
	v_cndmask_b32_e32 v180, v183, v0, vcc
	v_sub_f32_e32 v0, v183, v180
	v_exp_f32_e32 v0, v0
	s_nop 0
	v_mul_f32_e32 v71, v71, v0
	v_pk_mul_f32 v[32:33], v[32:33], v[0:1] op_sel_hi:[1,0]
	v_pk_mul_f32 v[30:31], v[30:31], v[0:1] op_sel_hi:[1,0]
	v_pk_mul_f32 v[28:29], v[28:29], v[0:1] op_sel_hi:[1,0]
	v_pk_mul_f32 v[26:27], v[26:27], v[0:1] op_sel_hi:[1,0]
	v_pk_mul_f32 v[24:25], v[24:25], v[0:1] op_sel_hi:[1,0]
	v_pk_mul_f32 v[22:23], v[22:23], v[0:1] op_sel_hi:[1,0]
	v_pk_mul_f32 v[20:21], v[20:21], v[0:1] op_sel_hi:[1,0]
	v_pk_mul_f32 v[18:19], v[18:19], v[0:1] op_sel_hi:[1,0]
	v_pk_mul_f32 v[16:17], v[16:17], v[0:1] op_sel_hi:[1,0]
	v_pk_mul_f32 v[14:15], v[14:15], v[0:1] op_sel_hi:[1,0]
	v_pk_mul_f32 v[12:13], v[12:13], v[0:1] op_sel_hi:[1,0]
	v_pk_mul_f32 v[10:11], v[10:11], v[0:1] op_sel_hi:[1,0]
	v_pk_mul_f32 v[8:9], v[8:9], v[0:1] op_sel_hi:[1,0]
	v_pk_mul_f32 v[6:7], v[6:7], v[0:1] op_sel_hi:[1,0]
	v_pk_mul_f32 v[4:5], v[4:5], v[0:1] op_sel_hi:[1,0]
	v_pk_mul_f32 v[2:3], v[2:3], v[0:1] op_sel_hi:[1,0]
	s_branch .LBB0_767

.LBB0_767:
	v_pk_add_f32 v[34:35], v[34:35], v[180:181] op_sel_hi:[1,0] neg_lo:[0,1] neg_hi:[0,1]
	v_pk_add_f32 v[36:37], v[36:37], v[180:181] op_sel_hi:[1,0] neg_lo:[0,1] neg_hi:[0,1]
	v_exp_f32_e32 v50, v34
	v_exp_f32_e32 v51, v35
	v_exp_f32_e32 v52, v36
	v_exp_f32_e32 v53, v37
	v_pk_add_f32 v[36:37], v[38:39], v[180:181] op_sel_hi:[1,0] neg_lo:[0,1] neg_hi:[0,1]
	v_pk_add_f32 v[34:35], v[50:51], 0 op_sel_hi:[1,0]
	v_exp_f32_e32 v38, v36
	v_exp_f32_e32 v39, v37
	v_pk_add_f32 v[36:37], v[40:41], v[180:181] op_sel_hi:[1,0] neg_lo:[0,1] neg_hi:[0,1]
	v_pk_add_f32 v[40:41], v[42:43], v[180:181] op_sel_hi:[1,0] neg_lo:[0,1] neg_hi:[0,1]
	v_exp_f32_e32 v36, v36
	v_exp_f32_e32 v37, v37
	v_exp_f32_e32 v40, v40
	v_exp_f32_e32 v41, v41
	v_pk_add_f32 v[42:43], v[44:45], v[180:181] op_sel_hi:[1,0] neg_lo:[0,1] neg_hi:[0,1]
	v_pk_add_f32 v[34:35], v[52:53], v[34:35]
	v_exp_f32_e32 v42, v42
	v_exp_f32_e32 v43, v43
	v_pk_add_f32 v[44:45], v[46:47], v[180:181] op_sel_hi:[1,0] neg_lo:[0,1] neg_hi:[0,1]
	v_pk_add_f32 v[34:35], v[38:39], v[34:35]
	v_exp_f32_e32 v44, v44
	v_exp_f32_e32 v45, v45
	v_pk_add_f32 v[46:47], v[48:49], v[180:181] op_sel_hi:[1,0] neg_lo:[0,1] neg_hi:[0,1]
	v_pk_add_f32 v[34:35], v[36:37], v[34:35]
	v_exp_f32_e32 v46, v46
	v_exp_f32_e32 v47, v47
	v_pk_add_f32 v[34:35], v[40:41], v[34:35]
	v_cvt_pk_bf16_f32 v37, v36, v37
	v_pk_add_f32 v[34:35], v[42:43], v[34:35]
	v_cvt_pk_bf16_f32 v36, v38, v39
	v_pk_add_f32 v[34:35], v[44:45], v[34:35]
	v_cvt_pk_bf16_f32 v73, v46, v47
	v_pk_add_f32 v[34:35], v[46:47], v[34:35]
	v_cvt_pk_bf16_f32 v72, v44, v45
	v_pk_add_f32 v[34:35], v[34:35], v[34:35] op_sel:[0,1] op_sel_hi:[1,0]
	v_cvt_pk_bf16_f32 v70, v40, v41
	v_mov_b32_e32 v0, v34
	s_nop 1
	v_permlane32_swap_b32_e32 v34, v0
	v_add_f32_e32 v0, v34, v0
	v_cvt_pk_bf16_f32 v35, v52, v53
	v_cvt_pk_bf16_f32 v34, v50, v51
	v_add_f32_e32 v169, v71, v0
	v_cvt_pk_bf16_f32 v71, v42, v43
	s_waitcnt vmcnt(11)
	v_mfma_f32_32x32x16_bf16 v[2:17], v[110:113], v[34:37], v[2:17]
	s_mov_b64 s[54:55], -1
	s_or_b64 s[50:51], s[50:51], exec
	s_waitcnt vmcnt(9)
	v_mfma_f32_32x32x16_bf16 v[18:33], v[102:105], v[34:37], v[18:33]
	s_nop 7
	v_mov_b64_e32 v[64:65], v[16:17]
	v_mov_b64_e32 v[62:63], v[14:15]
	v_mov_b64_e32 v[60:61], v[12:13]
	v_mov_b64_e32 v[58:59], v[10:11]
	v_mov_b64_e32 v[56:57], v[8:9]
	v_mov_b64_e32 v[54:55], v[6:7]
	v_mov_b64_e32 v[52:53], v[4:5]
	v_mov_b64_e32 v[48:49], v[32:33]
	v_mov_b64_e32 v[50:51], v[2:3]
	v_mov_b64_e32 v[46:47], v[30:31]
	v_mov_b64_e32 v[44:45], v[28:29]
	v_mov_b64_e32 v[42:43], v[26:27]
	v_mov_b64_e32 v[40:41], v[24:25]
	v_mov_b64_e32 v[38:39], v[22:23]
	v_mov_b64_e32 v[36:37], v[20:21]
	v_mov_b64_e32 v[34:35], v[18:19]
	v_mfma_f32_32x32x16_bf16 v[50:65], v[106:109], v[70:73], v[50:65]
	s_waitcnt vmcnt(8)
	v_mfma_f32_32x32x16_bf16 v[34:49], v[98:101], v[70:73], v[34:49]
	s_and_saveexec_b64 s[52:53], s[40:41]
	s_cbranch_execz .LBB0_763
	v_add_u32_e32 v184, 1, v182
	v_cmp_lt_u32_e32 vcc, v182, v159
	v_mov_b32_e32 v3, v1
	s_waitcnt vmcnt(4)
	ds_read_b128 v[66:69], v234 offset:4096
	ds_read_b128 v[154:157], v235 offset:4096
	ds_read_b128 v[150:153], v236 offset:4096
	ds_read_b128 v[146:149], v237 offset:4096
	s_waitcnt lgkmcnt(3)
	v_mfma_f32_32x32x16_bf16 v[66:81], v[66:69], v[94:97], 0
	v_cndmask_b32_e32 v2, v182, v184, vcc
	v_lshlrev_b32_e32 v0, 5, v2
	v_lshl_add_u64 v[4:5], v[174:175], 0, v[0:1]
	v_mad_u64_u32 v[6:7], s[40:41], v4, s80, v[178:179]
	v_mov_b32_e32 v0, v7
	v_mad_u64_u32 v[4:5], s[40:41], v5, s80, v[0:1]
	v_mov_b32_e32 v7, v4
	v_lshlrev_b64 v[2:3], 12, v[2:3]
	v_lshl_add_u64 v[2:3], v[176:177], 0, v[2:3]
	s_add_u32 m0, s98, 0x0
	v_mad_i64_i32 v[232:233], s[100:101], v224, s99, v[6:7]
	v_add_u32_e32 v232, v228, v232
	global_load_lds_dwordx4 v[232:233], off
	s_add_u32 m0, s98, 0x400
	v_mad_i64_i32 v[232:233], s[100:101], v225, s99, v[6:7]
	v_add_u32_e32 v232, v229, v232
	global_load_lds_dwordx4 v[232:233], off
	s_add_u32 m0, s98, 0x800
	v_mad_i64_i32 v[232:233], s[100:101], v226, s99, v[6:7]
	v_add_u32_e32 v232, v228, v232
	global_load_lds_dwordx4 v[232:233], off
	s_add_u32 m0, s98, 0xc00
	v_mad_i64_i32 v[232:233], s[100:101], v227, s99, v[6:7]
	v_add_u32_e32 v232, v229, v232
	global_load_lds_dwordx4 v[232:233], off
	global_load_dwordx4 v[110:113], v[2:3], off
	global_load_dwordx4 v[106:109], v[2:3], off offset:16
	global_load_dwordx4 v[102:105], v[2:3], off offset:2048
	global_load_dwordx4 v[98:101], v[2:3], off offset:2064
	s_waitcnt lgkmcnt(2)
	v_mfma_f32_32x32x16_bf16 v[66:81], v[154:157], v[86:89], v[66:81]
	v_cmp_ge_u32_e64 s[40:41], v182, v159
	s_waitcnt lgkmcnt(1)
	v_mfma_f32_32x32x16_bf16 v[66:81], v[150:153], v[82:85], v[66:81]
	s_waitcnt lgkmcnt(0)
	v_mfma_f32_32x32x16_bf16 v[66:81], v[146:149], v[90:93], v[66:81]
	s_nop 11
	v_max_f32_e32 v0, v69, v69
	v_max_f32_e32 v2, v68, v68
	v_max_f32_e32 v0, v2, v0
	v_max_f32_e32 v2, v73, v73
	v_max_f32_e32 v3, v72, v72
	v_max_f32_e32 v2, v3, v2
	v_max_f32_e32 v3, v75, v75
	v_max_f32_e32 v4, v74, v74
	v_max_f32_e32 v3, v4, v3
	v_max_f32_e32 v4, v77, v77
	v_max_f32_e32 v5, v76, v76
	v_max_f32_e32 v4, v5, v4
	v_max_f32_e32 v5, v81, v81
	v_max_f32_e32 v6, v80, v80
	v_max_f32_e32 v5, v6, v5
	v_max3_f32 v5, v78, v79, v5
	v_max3_f32 v0, v66, v67, v0
	v_max3_f32 v2, v70, v71, v2
	v_max3_f32 v3, v3, v4, v5
	v_max3_f32 v0, v0, v2, v3
	v_mov_b32_e32 v2, v0
	s_nop 1
	v_permlane32_swap_b32_e32 v0, v2
	v_max_f32_e32 v2, v2, v2
	v_max_f32_e32 v0, v0, v0
	v_max_f32_e32 v0, v0, v2
	v_add_f32_e32 v2, 0x41800000, v180
	v_cmp_gt_f32_e32 vcc, v0, v2
	s_cbranch_vccnz .LBB0_761
	v_mov_b64_e32 v[182:183], v[180:181]
	v_mov_b32_e32 v0, v169
	v_mov_b32_e32 v183, v180
	v_mov_b32_e32 v2, v50
	v_mov_b32_e32 v3, v51
	v_mov_b32_e32 v4, v52
	v_mov_b32_e32 v5, v53
	v_mov_b32_e32 v6, v54
	v_mov_b32_e32 v7, v55
	v_mov_b32_e32 v8, v56
	v_mov_b32_e32 v9, v57
	v_mov_b32_e32 v10, v58
	v_mov_b32_e32 v11, v59
	v_mov_b32_e32 v12, v60
	v_mov_b32_e32 v13, v61
	v_mov_b32_e32 v14, v62
	v_mov_b32_e32 v15, v63
	v_mov_b32_e32 v16, v64
	v_mov_b32_e32 v17, v65
	v_mov_b32_e32 v18, v34
	v_mov_b32_e32 v19, v35
	v_mov_b32_e32 v20, v36
	v_mov_b32_e32 v21, v37
	v_mov_b32_e32 v22, v38
	v_mov_b32_e32 v23, v39
	v_mov_b32_e32 v24, v40
	v_mov_b32_e32 v25, v41
	v_mov_b32_e32 v26, v42
	v_mov_b32_e32 v27, v43
	v_mov_b32_e32 v28, v44
	v_mov_b32_e32 v29, v45
	v_mov_b32_e32 v30, v46
	v_mov_b32_e32 v31, v47
	v_mov_b32_e32 v32, v48
	v_mov_b32_e32 v33, v49
	s_branch .LBB0_762

.LBB0_849:
	s_or_b64 exec, exec, s[44:45]
	v_cmp_lt_i32_e32 vcc, -1, v162
	v_lshlrev_b32_e32 v0, 2, v39
	s_and_saveexec_b64 s[38:39], vcc
	s_xor_b64 s[40:41], exec, s[38:39]
	s_cbranch_execz .LBB0_846
	v_readlane_b32 s12, v253, 2
	v_and_b32_e32 v0, 63, v35
	s_lshl_b64 s[38:39], s[42:43], 19
	v_readlane_b32 s22, v253, 12
	v_mov_b32_e32 v35, v1
	v_readlane_b32 s23, v253, 13
	s_add_u32 s38, s22, s38
	v_lshl_add_u64 v[34:35], s[0:1], 0, v[34:35]
	s_addc_u32 s39, s23, s39
	v_lshlrev_b32_e32 v0, 5, v0
	v_readlane_b32 s12, v254, 43
	v_or_b32_e32 v34, v34, v38
	v_mov_b64_e32 v[36:37], s[66:67]
	v_lshl_add_u64 v[166:167], s[38:39], 0, v[0:1]
	v_or_b32_e32 v0, s12, v40
	v_mad_u64_u32 v[36:37], s[38:39], v34, s80, v[36:37]
	v_mad_i32_i24 v37, v35, s80, v37
	v_lshlrev_b32_e32 v34, 1, v0
	v_mov_b32_e32 v35, v1
	v_mov_b32_e32 v163, v1
	v_lshl_add_u64 v[36:37], v[36:37], 0, v[34:35]
	v_lshlrev_b64 v[40:41], 12, v[162:163]
	v_lshl_add_u64 v[40:41], v[166:167], 0, v[40:41]
	v_and_b32_e32 v238, 63, v199
	v_lshrrev_b32_e32 v239, 3, v238
	v_and_b32_e32 v240, 31, v238
	v_sub_u32_e32 v224, v239, v240
	v_add_u32_e32 v225, 8, v224
	v_add_u32_e32 v226, 16, v224
	v_add_u32_e32 v227, 24, v224
	v_lshrrev_b32_e32 v241, 5, v238
	v_and_b32_e32 v242, 7, v238
	v_lshrrev_b32_e32 v243, 4, v238
	v_xor_b32_e32 v228, v242, v243
	v_xor_b32_e32 v229, 4, v228
	v_sub_u32_e32 v228, v228, v241
	v_sub_u32_e32 v229, v229, v241
	v_lshlrev_b32_e32 v228, 4, v228
	v_lshlrev_b32_e32 v229, 4, v229
	v_lshrrev_b32_e32 v250, 6, v199
	v_lshlrev_b32_e32 v250, 13, v250
	v_bfe_u32 v251, v238, 1, 3
	v_xor_b32_e32 v251, v251, v241
	v_lshlrev_b32_e32 v251, 4, v251
	v_lshl_add_u32 v251, v240, 7, v251
	v_add_u32_e32 v234, v250, v251
	v_xor_b32_e32 v235, 0x20, v234
	v_xor_b32_e32 v236, 0x40, v234
	v_xor_b32_e32 v237, 0x60, v234
	v_readfirstlane_b32 s98, v250
	s_mov_b32 s99, 0x1c00
	s_add_u32 m0, s98, 0x0
	v_mad_i64_i32 v[232:233], s[100:101], v224, s99, v[36:37]
	v_add_u32_e32 v232, v228, v232
	global_load_lds_dwordx4 v[232:233], off
	s_add_u32 m0, s98, 0x400
	v_mad_i64_i32 v[232:233], s[100:101], v225, s99, v[36:37]
	v_add_u32_e32 v232, v229, v232
	global_load_lds_dwordx4 v[232:233], off
	s_add_u32 m0, s98, 0x800
	v_mad_i64_i32 v[232:233], s[100:101], v226, s99, v[36:37]
	v_add_u32_e32 v232, v228, v232
	global_load_lds_dwordx4 v[232:233], off
	s_add_u32 m0, s98, 0xc00
	v_mad_i64_i32 v[232:233], s[100:101], v227, s99, v[36:37]
	v_add_u32_e32 v232, v229, v232
	global_load_lds_dwordx4 v[232:233], off
	global_load_dwordx4 v[110:113], v[40:41], off
	global_load_dwordx4 v[106:109], v[40:41], off offset:16
	global_load_dwordx4 v[102:105], v[40:41], off offset:2048
	global_load_dwordx4 v[98:101], v[40:41], off offset:2064
	v_lshl_add_u64 v[170:171], s[66:67], 0, v[34:35]
	v_and_b32_e32 v34, 0x7ffffff8, v162
	v_lshlrev_b32_e32 v0, 2, v39
	v_cmp_ne_u32_e32 vcc, v34, v162
	v_or_b32_e32 v163, 0x186a0, v0
	v_or_b32_e32 v172, 0x186a1, v0
	v_or_b32_e32 v173, 0x186a2, v0
	v_or_b32_e32 v174, 0x186a3, v0
	v_or_b32_e32 v175, 0x186a8, v0
	v_or_b32_e32 v176, 0x186a9, v0
	v_or_b32_e32 v177, 0x186aa, v0
	v_or_b32_e32 v178, 0x186ab, v0
	v_or_b32_e32 v179, 0x186b0, v0
	v_or_b32_e32 v180, 0x186b1, v0
	v_or_b32_e32 v181, 0x186b2, v0
	v_or_b32_e32 v182, 0x186b3, v0
	v_or_b32_e32 v183, 0x186b8, v0
	v_or_b32_e32 v184, 0x186b9, v0
	v_or_b32_e32 v185, 0x186ba, v0
	v_or_b32_e32 v186, 0x186bb, v0
	v_or_b32_e32 v168, s0, v38
	v_mov_b32_e32 v169, s1
	v_or_b32_e32 v187, 0x186a0, v38
	v_cndmask_b32_e32 v188, -1, v34, vcc
	s_mov_b64 s[44:45], 0
	v_mov_b32_e32 v190, v162
	v_readlane_b32 s13, v253, 3
	v_readlane_b32 s14, v253, 4
	v_readlane_b32 s15, v253, 5
	v_readlane_b32 s16, v253, 6
	v_readlane_b32 s17, v253, 7
	v_readlane_b32 s18, v253, 8
	v_readlane_b32 s19, v253, 9
	v_readlane_b32 s20, v253, 10
	v_readlane_b32 s21, v253, 11
	v_readlane_b32 s24, v253, 14
	v_readlane_b32 s25, v253, 15
	v_readlane_b32 s26, v253, 16
	v_readlane_b32 s27, v253, 17
	s_branch .LBB0_854

.LBB0_854:
	v_add_u32_e32 v34, 1, v190
	v_cmp_lt_i32_e32 vcc, v34, v162
	s_nop 1
	v_cndmask_b32_e32 v34, -1, v34, vcc
	v_cmp_eq_u32_e32 vcc, v190, v162
	s_nop 1
	v_cndmask_b32_e32 v71, v34, v188, vcc
	v_cmp_gt_i32_e64 s[0:1], 0, v71
	v_cmp_lt_i32_e64 s[38:39], -1, v71
	s_nop 0
	v_cndmask_b32_e64 v50, v71, v190, s[0:1]
	v_lshlrev_b32_e32 v34, 5, v50
	v_ashrrev_i32_e32 v35, 31, v34
	v_lshl_add_u64 v[52:53], v[168:169], 0, v[34:35]
	v_mad_u64_u32 v[54:55], s[0:1], v52, s80, v[170:171]
	v_mov_b32_e32 v52, v55
	v_mad_u64_u32 v[52:53], s[0:1], v53, s80, v[52:53]
	v_ashrrev_i32_e32 v51, 31, v50
	v_mov_b32_e32 v55, v52
	v_lshlrev_b64 v[50:51], 12, v[50:51]
	v_lshl_add_u64 v[50:51], v[166:167], 0, v[50:51]
	s_add_u32 m0, s98, 0x1000
	v_mad_i64_i32 v[232:233], s[100:101], v224, s99, v[54:55]
	v_add_u32_e32 v232, v228, v232
	global_load_lds_dwordx4 v[232:233], off
	s_add_u32 m0, s98, 0x1400
	v_mad_i64_i32 v[232:233], s[100:101], v225, s99, v[54:55]
	v_add_u32_e32 v232, v229, v232
	global_load_lds_dwordx4 v[232:233], off
	s_add_u32 m0, s98, 0x1800
	v_mad_i64_i32 v[232:233], s[100:101], v226, s99, v[54:55]
	v_add_u32_e32 v232, v228, v232
	global_load_lds_dwordx4 v[232:233], off
	s_add_u32 m0, s98, 0x1c00
	v_mad_i64_i32 v[232:233], s[100:101], v227, s99, v[54:55]
	v_add_u32_e32 v232, v229, v232
	global_load_lds_dwordx4 v[232:233], off
	global_load_dwordx4 v[142:145], v[50:51], off
	global_load_dwordx4 v[126:129], v[50:51], off offset:16
	global_load_dwordx4 v[118:121], v[50:51], off offset:2048
	global_load_dwordx4 v[114:117], v[50:51], off offset:2064
	s_waitcnt vmcnt(12)
	ds_read_b128 v[138:141], v234
	ds_read_b128 v[130:133], v235
	ds_read_b128 v[122:125], v236
	ds_read_b128 v[134:137], v237
	s_waitcnt lgkmcnt(3)
	v_mfma_f32_32x32x16_bf16 v[34:49], v[138:141], v[90:93], 0
	v_cndmask_b32_e32 v50, v219, v187, vcc
	v_cmp_gt_u32_e32 vcc, s9, v50
	s_waitcnt lgkmcnt(2)
	v_mfma_f32_32x32x16_bf16 v[34:49], v[130:133], v[82:85], v[34:49]
	s_waitcnt lgkmcnt(1)
	v_mfma_f32_32x32x16_bf16 v[34:49], v[122:125], v[86:89], v[34:49]
	s_waitcnt lgkmcnt(0)
	v_mfma_f32_32x32x16_bf16 v[34:49], v[134:137], v[94:97], v[34:49]
	s_cbranch_vccz .LBB0_856
	v_cmp_le_u32_e32 vcc, v163, v50
	s_nop 9
	v_cndmask_b32_e32 v34, v212, v34, vcc
	v_cmp_le_u32_e32 vcc, v172, v50
	s_nop 1
	v_cndmask_b32_e32 v35, v212, v35, vcc
	v_cmp_le_u32_e32 vcc, v173, v50
	s_nop 1
	v_cndmask_b32_e32 v36, v212, v36, vcc
	v_cmp_le_u32_e32 vcc, v174, v50
	s_nop 1
	v_cndmask_b32_e32 v37, v212, v37, vcc
	v_cmp_le_u32_e32 vcc, v175, v50
	s_nop 1
	v_cndmask_b32_e32 v38, v212, v38, vcc
	v_cmp_le_u32_e32 vcc, v176, v50
	s_nop 1
	v_cndmask_b32_e32 v39, v212, v39, vcc
	v_cmp_le_u32_e32 vcc, v177, v50
	s_nop 1
	v_cndmask_b32_e32 v40, v212, v40, vcc
	v_cmp_le_u32_e32 vcc, v178, v50
	s_nop 1
	v_cndmask_b32_e32 v41, v212, v41, vcc
	v_cmp_le_u32_e32 vcc, v179, v50
	s_nop 1
	v_cndmask_b32_e32 v42, v212, v42, vcc
	v_cmp_le_u32_e32 vcc, v180, v50
	s_nop 1
	v_cndmask_b32_e32 v43, v212, v43, vcc
	v_cmp_le_u32_e32 vcc, v181, v50
	s_nop 1
	v_cndmask_b32_e32 v44, v212, v44, vcc
	v_cmp_le_u32_e32 vcc, v182, v50
	s_nop 1
	v_cndmask_b32_e32 v45, v212, v45, vcc
	v_cmp_le_u32_e32 vcc, v183, v50
	s_nop 1
	v_cndmask_b32_e32 v46, v212, v46, vcc
	v_cmp_le_u32_e32 vcc, v184, v50
	s_nop 1
	v_cndmask_b32_e32 v47, v212, v47, vcc
	v_cmp_le_u32_e32 vcc, v185, v50
	s_nop 1
	v_cndmask_b32_e32 v48, v212, v48, vcc
	v_cmp_le_u32_e32 vcc, v186, v50
	s_nop 1
	v_cndmask_b32_e32 v49, v212, v49, vcc

.LBB0_858:
	v_pk_add_f32 v[34:35], v[34:35], v[164:165] op_sel_hi:[1,0] neg_lo:[0,1] neg_hi:[0,1]
	v_pk_add_f32 v[36:37], v[36:37], v[164:165] op_sel_hi:[1,0] neg_lo:[0,1] neg_hi:[0,1]
	v_exp_f32_e32 v34, v34
	v_exp_f32_e32 v35, v35
	v_exp_f32_e32 v36, v36
	v_exp_f32_e32 v37, v37
	v_pk_add_f32 v[38:39], v[38:39], v[164:165] op_sel_hi:[1,0] neg_lo:[0,1] neg_hi:[0,1]
	v_pk_add_f32 v[40:41], v[40:41], v[164:165] op_sel_hi:[1,0] neg_lo:[0,1] neg_hi:[0,1]
	v_exp_f32_e32 v38, v38
	v_exp_f32_e32 v39, v39
	v_exp_f32_e32 v40, v40
	v_exp_f32_e32 v41, v41
	v_pk_add_f32 v[42:43], v[42:43], v[164:165] op_sel_hi:[1,0] neg_lo:[0,1] neg_hi:[0,1]
	v_pk_add_f32 v[50:51], v[34:35], 0 op_sel_hi:[1,0]
	v_exp_f32_e32 v42, v42
	v_exp_f32_e32 v43, v43
	v_pk_add_f32 v[44:45], v[44:45], v[164:165] op_sel_hi:[1,0] neg_lo:[0,1] neg_hi:[0,1]
	v_pk_add_f32 v[50:51], v[36:37], v[50:51]
	v_exp_f32_e32 v44, v44
	v_exp_f32_e32 v45, v45
	v_pk_add_f32 v[46:47], v[46:47], v[164:165] op_sel_hi:[1,0] neg_lo:[0,1] neg_hi:[0,1]
	v_pk_add_f32 v[50:51], v[38:39], v[50:51]
	v_exp_f32_e32 v46, v46
	v_exp_f32_e32 v47, v47
	v_pk_add_f32 v[48:49], v[48:49], v[164:165] op_sel_hi:[1,0] neg_lo:[0,1] neg_hi:[0,1]
	v_pk_add_f32 v[50:51], v[40:41], v[50:51]
	v_exp_f32_e32 v48, v48
	v_exp_f32_e32 v49, v49
	v_pk_add_f32 v[50:51], v[42:43], v[50:51]
	v_cvt_pk_bf16_f32 v53, v40, v41
	v_pk_add_f32 v[50:51], v[44:45], v[50:51]
	v_cvt_pk_bf16_f32 v52, v38, v39
	v_pk_add_f32 v[50:51], v[46:47], v[50:51]
	v_cvt_pk_bf16_f32 v75, v48, v49
	v_pk_add_f32 v[50:51], v[48:49], v[50:51]
	v_cvt_pk_bf16_f32 v74, v46, v47
	v_pk_add_f32 v[50:51], v[50:51], v[50:51] op_sel:[0,1] op_sel_hi:[1,0]
	v_cvt_pk_bf16_f32 v73, v44, v45
	v_mov_b32_e32 v51, v50
	s_nop 1
	v_permlane32_swap_b32_e32 v50, v51
	v_add_f32_e32 v50, v50, v51
	v_add_f32_e32 v189, v70, v50
	v_cvt_pk_bf16_f32 v51, v36, v37
	v_cvt_pk_bf16_f32 v50, v34, v35
	v_cvt_pk_bf16_f32 v72, v42, v43
	s_mov_b64 s[0:1], -1
	s_waitcnt vmcnt(11)
	v_mfma_f32_32x32x16_bf16 v[18:33], v[110:113], v[50:53], v[18:33]
	s_or_b64 s[46:47], s[46:47], exec
	s_waitcnt vmcnt(9)
	v_mfma_f32_32x32x16_bf16 v[2:17], v[102:105], v[50:53], v[2:17]
	s_nop 8
	v_mov_b64_e32 v[48:49], v[32:33]
	v_mov_b64_e32 v[46:47], v[30:31]
	v_mov_b64_e32 v[44:45], v[28:29]
	v_mov_b64_e32 v[42:43], v[26:27]
	v_mov_b64_e32 v[40:41], v[24:25]
	v_mov_b64_e32 v[38:39], v[22:23]
	v_mov_b64_e32 v[36:37], v[20:21]
	v_mov_b64_e32 v[64:65], v[16:17]
	v_mov_b64_e32 v[34:35], v[18:19]
	v_mov_b64_e32 v[62:63], v[14:15]
	v_mov_b64_e32 v[60:61], v[12:13]
	v_mov_b64_e32 v[58:59], v[10:11]
	v_mov_b64_e32 v[56:57], v[8:9]
	v_mov_b64_e32 v[54:55], v[6:7]
	v_mov_b64_e32 v[52:53], v[4:5]
	v_mov_b64_e32 v[50:51], v[2:3]
	v_mfma_f32_32x32x16_bf16 v[34:49], v[106:109], v[72:75], v[34:49]
	s_waitcnt vmcnt(8)
	v_mfma_f32_32x32x16_bf16 v[50:65], v[98:101], v[72:75], v[50:65]
	s_and_saveexec_b64 s[48:49], s[38:39]
	s_cbranch_execz .LBB0_853
	v_add_u32_e32 v2, 1, v71
	v_cmp_lt_i32_e32 vcc, v2, v162
	s_nop 1
	v_cndmask_b32_e32 v2, -1, v2, vcc
	v_cmp_eq_u32_e32 vcc, v71, v162
	s_nop 1
	v_cndmask_b32_e32 v190, v2, v188, vcc
	v_cmp_lt_i32_e64 s[0:1], -1, v190
	v_cmp_gt_i32_e64 s[38:39], 0, v190
	s_nop 0
	v_cndmask_b32_e64 v2, v71, v190, s[0:1]
	v_lshlrev_b32_e32 v4, 5, v2
	v_ashrrev_i32_e32 v5, 31, v4
	v_lshl_add_u64 v[4:5], v[168:169], 0, v[4:5]
	v_mad_u64_u32 v[6:7], s[0:1], v4, s80, v[170:171]
	v_mov_b32_e32 v4, v7
	v_mad_u64_u32 v[4:5], s[0:1], v5, s80, v[4:5]
	v_ashrrev_i32_e32 v3, 31, v2
	v_mov_b32_e32 v7, v4
	v_lshlrev_b64 v[2:3], 12, v[2:3]
	v_lshl_add_u64 v[2:3], v[166:167], 0, v[2:3]
	s_add_u32 m0, s98, 0x0
	v_mad_i64_i32 v[232:233], s[100:101], v224, s99, v[6:7]
	v_add_u32_e32 v232, v228, v232
	global_load_lds_dwordx4 v[232:233], off
	s_add_u32 m0, s98, 0x400
	v_mad_i64_i32 v[232:233], s[100:101], v225, s99, v[6:7]
	v_add_u32_e32 v232, v229, v232
	global_load_lds_dwordx4 v[232:233], off
	s_add_u32 m0, s98, 0x800
	v_mad_i64_i32 v[232:233], s[100:101], v226, s99, v[6:7]
	v_add_u32_e32 v232, v228, v232
	global_load_lds_dwordx4 v[232:233], off
	s_add_u32 m0, s98, 0xc00
	v_mad_i64_i32 v[232:233], s[100:101], v227, s99, v[6:7]
	v_add_u32_e32 v232, v229, v232
	global_load_lds_dwordx4 v[232:233], off
	global_load_dwordx4 v[110:113], v[2:3], off
	global_load_dwordx4 v[106:109], v[2:3], off offset:16
	global_load_dwordx4 v[102:105], v[2:3], off offset:2048
	global_load_dwordx4 v[98:101], v[2:3], off offset:2064
	s_waitcnt vmcnt(12)
	ds_read_b128 v[66:69], v234 offset:4096
	ds_read_b128 v[154:157], v235 offset:4096
	ds_read_b128 v[150:153], v236 offset:4096
	ds_read_b128 v[146:149], v237 offset:4096
	s_waitcnt lgkmcnt(3)
	v_mfma_f32_32x32x16_bf16 v[66:81], v[66:69], v[90:93], 0
	v_cndmask_b32_e32 v2, v219, v187, vcc
	v_cmp_gt_u32_e32 vcc, s9, v2
	s_waitcnt lgkmcnt(2)
	v_mfma_f32_32x32x16_bf16 v[66:81], v[154:157], v[82:85], v[66:81]
	s_waitcnt lgkmcnt(1)
	v_mfma_f32_32x32x16_bf16 v[66:81], v[150:153], v[86:89], v[66:81]
	s_waitcnt lgkmcnt(0)
	v_mfma_f32_32x32x16_bf16 v[66:81], v[146:149], v[94:97], v[66:81]
	s_cbranch_vccz .LBB0_861
	v_cmp_le_u32_e32 vcc, v163, v2
	s_nop 9
	v_cndmask_b32_e32 v66, v212, v66, vcc
	v_cmp_le_u32_e32 vcc, v172, v2
	s_nop 1
	v_cndmask_b32_e32 v67, v212, v67, vcc
	v_cmp_le_u32_e32 vcc, v173, v2
	s_nop 1
	v_cndmask_b32_e32 v68, v212, v68, vcc
	v_cmp_le_u32_e32 vcc, v174, v2
	s_nop 1
	v_cndmask_b32_e32 v69, v212, v69, vcc
	v_cmp_le_u32_e32 vcc, v175, v2
	s_nop 1
	v_cndmask_b32_e32 v70, v212, v70, vcc
	v_cmp_le_u32_e32 vcc, v176, v2
	s_nop 1
	v_cndmask_b32_e32 v71, v212, v71, vcc
	v_cmp_le_u32_e32 vcc, v177, v2
	s_nop 1
	v_cndmask_b32_e32 v72, v212, v72, vcc
	v_cmp_le_u32_e32 vcc, v178, v2
	s_nop 1
	v_cndmask_b32_e32 v73, v212, v73, vcc
	v_cmp_le_u32_e32 vcc, v179, v2
	s_nop 1
	v_cndmask_b32_e32 v74, v212, v74, vcc
	v_cmp_le_u32_e32 vcc, v180, v2
	s_nop 1
	v_cndmask_b32_e32 v75, v212, v75, vcc
	v_cmp_le_u32_e32 vcc, v181, v2
	s_nop 1
	v_cndmask_b32_e32 v76, v212, v76, vcc
	v_cmp_le_u32_e32 vcc, v182, v2
	s_nop 1
	v_cndmask_b32_e32 v77, v212, v77, vcc
	v_cmp_le_u32_e32 vcc, v183, v2
	s_nop 1
	v_cndmask_b32_e32 v78, v212, v78, vcc
	v_cmp_le_u32_e32 vcc, v184, v2
	s_nop 1
	v_cndmask_b32_e32 v79, v212, v79, vcc
	v_cmp_le_u32_e32 vcc, v185, v2
	s_nop 1
	v_cndmask_b32_e32 v80, v212, v80, vcc
	v_cmp_le_u32_e32 vcc, v186, v2
	s_nop 1
	v_cndmask_b32_e32 v81, v212, v81, vcc
